# v72 + first K-step MFMAs take inline 0 as SrcC (peeled P1/P2 per tile), accumulator zeroing v_movs removed in win/gu/down
# speedup vs baseline: 1.0060x; 1.0060x over previous
; template <class Epi>
; DI void gemm_phase(LAS unsigned char* lds, const Gemm g, const StaticOrder& S, const Epi& E) {
;     ...
;         const bool has_next = S.next(ui + 1, nxt);
;         const char* nA = has_next ? (const char*)g.A + (size_t)nxt.pm * tstep : cA; const char* nB = has_next ? (const char*)g.Bt + (size_t)nxt.pn * tstep : cB;
;     ...
;         for (int a = 0; a < 2; ++a)
; #pragma unroll
;             for (int b = 0; b < 2; ++b)
; #pragma unroll
;                 for (int m = 0; m < 4; ++m)
; #pragma unroll
;                     for (int n = 0; n < 2; ++n) acc[a][b][m][n] = (f32x4){0.f, 0.f, 0.f, 0.f};
.LBB0_91:
	s_ashr_i32 s55, s54, 31
	s_lshl_b64 s[22:23], s[54:55], 19
	s_add_u32 s56, s24, s22
	s_addc_u32 s57, s25, s23
	s_and_b64 s[22:23], s[4:5], exec
	s_cselect_b32 s7, s57, s65
	s_cselect_b32 s17, s56, s64
	s_ashr_i32 s53, s52, 31
	s_lshl_b64 s[22:23], s[52:53], 19
	s_add_u32 s58, s30, s22
	s_addc_u32 s59, s31, s23
	s_and_b64 s[22:23], s[4:5], exec
	s_cselect_b32 s22, s59, s63
	s_cselect_b32 s23, s58, s62
	s_add_u32 s42, s62, 0x100
	s_addc_u32 s43, s63, 0
	s_add_u32 s62, s64, 0x40080
	s_addc_u32 s63, s65, 0
	s_mov_b32 s53, -2
	s_waitcnt vmcnt(0)
	v_readfirstlane_b32 s101, v242
	s_nop 3
	s_lshr_b32 s101, s101, 8
	s_cmp_eq_u32 s101, 0
	s_cbranch_scc0 .Lsp_5
	s_setprio 1
; #define PG8_STAGE(bufoff, gbase, voff) do { _Pragma("unroll") for (int _i = 0; _i < 2; ++_i) \
;         __builtin_amdgcn_global_load_lds((const unsigned*)((const char*)(gbase) + (voff)[_i]), (LAS unsigned*)(lds + (bufoff) + ldsw + _i * 8192), 16, 0, 0); } while (0)
; #define PG8_LDA(dst, b, h) do { _Pragma("unroll") for (int m = 0; m < 4; ++m) _Pragma("unroll") for (int k = 0; k < 2; ++k) dst[m][k] = *(const LAS bf16x8*)(lds + PG8_SA(b, h) + aoff + m * 2048 + k * 1024); } while (0)
; #define PG8_LDB(dst, b, h) do { _Pragma("unroll") for (int n = 0; n < 2; ++n) _Pragma("unroll") for (int k = 0; k < 2; ++k) dst[n][k] = *(const LAS bf16x8*)(lds + PG8_SB(b, h) + boff + n * 2048 + k * 1024); } while (0)
; #define PG8_MMA(ai, bj, At, Bt) do { __builtin_amdgcn_s_setprio(1); _Pragma("unroll") for (int m = 0; m < 4; ++m) _Pragma("unroll") for (int n = 0; n < 2; ++n) _Pragma("unroll") for (int k = 0; k < 2; ++k) \
;         acc[ai][bj][m][n] = __builtin_amdgcn_mfma_f32_16x16x32_bf16(Bt[n][k], At[m][k], acc[ai][bj][m][n], 0, 0, 0); __builtin_amdgcn_s_setprio(0); } while (0)
; #define PG8_WAIT_V(n) asm volatile("s_waitcnt vmcnt(" #n ")" ::: "memory")
; #define PG8_WAIT_L(n) asm volatile("s_waitcnt lgkmcnt(" #n ")" ::: "memory")
; #define PG8_BAR __builtin_amdgcn_s_barrier()
; #define PG8_SCHED __builtin_amdgcn_sched_barrier(0)
; template <class Epi>
; DI void gemm_phase(LAS unsigned char* lds, const Gemm g, const StaticOrder& S, const Epi& E) {
;     ...
;             const bool last = (t == nt - 2);
;             const char* a1 = cA + (size_t)(t + 1) * kstep;
;             const char* a2 = last ? nA : cA + (size_t)(t + 2) * kstep; const char* b2 = last ? nB : cB + (size_t)(t + 2) * kstep;
;             const char* a3 = a2 + kstep; const char* b3 = b2 + kstep;
;             PG8_LDB(B0, 0, 0); PG8_LDB(B1, 0, 1); PG8_SCHED; PG8_LDA(At, 0, 0); PG8_STAGE(PG8_SA(1, 1), a1 + hstep, voffA);
;             PG8_WAIT_V(8); PG8_WAIT_L(0); PG8_BAR; PG8_MMA(0, 0, At, B0); PG8_MMA(0, 1, At, B1); PG8_BAR; PG8_SCHED;
;             PG8_LDA(At, 0, 1); PG8_STAGE(PG8_SB(0, 0), b2, voffB); PG8_STAGE(PG8_SB(0, 1), b2 + hstep, voffB); PG8_STAGE(PG8_SA(0, 0), a2, voffA);
;             PG8_WAIT_V(8); PG8_WAIT_L(0); PG8_BAR; PG8_MMA(1, 0, At, B0); PG8_MMA(1, 1, At, B1); PG8_BAR; PG8_SCHED;
.Lsp_5:
	s_add_u32 s18, s62, 0xfffc0080
	s_addc_u32 s19, s63, -1
	s_add_i32 s55, 0, 0x10000
	s_cmp_eq_u32 s53, 12
	s_cselect_b32 s67, s7, s19
	s_cselect_b32 s66, s17, s18
	s_cselect_b32 s65, s22, s43
	s_cselect_b32 s64, s23, s42
	s_add_i32 s18, 0, 0x14000
	v_add_u32_e32 v118, s55, v195
	v_add_u32_e32 v158, s18, v195
	ds_read_b128 v[66:69], v118
	ds_read_b128 v[78:81], v118 offset:1024
	ds_read_b128 v[98:101], v118 offset:2048
	ds_read_b128 v[118:121], v118 offset:3072
	ds_read_b128 v[138:141], v158
	ds_read_b128 v[142:145], v158 offset:1024
	ds_read_b128 v[154:157], v158 offset:2048
	ds_read_b128 v[158:161], v158 offset:3072
	v_lshl_add_u64 v[200:201], s[62:63], 0, v[222:223]
	s_add_i32 m0, s37, 0xc000
	ds_read_b128 v[162:165], v246
	ds_read_b128 v[166:169], v246 offset:1024
	ds_read_b128 v[170:173], v246 offset:2048
	ds_read_b128 v[174:177], v246 offset:3072
	ds_read_b128 v[178:181], v246 offset:4096
	ds_read_b128 v[182:185], v246 offset:5120
	ds_read_b128 v[186:189], v246 offset:6144
	ds_read_b128 v[190:193], v246 offset:7168
	global_load_lds_dwordx4 v[200:201], off
	v_lshl_add_u64 v[200:201], s[62:63], 0, v[220:221]
	s_add_i32 m0, s37, 0xe000
	s_nop 0
	global_load_lds_dwordx4 v[200:201], off
	s_waitcnt vmcnt(8)
	s_waitcnt lgkmcnt(0)
	s_barrier
	s_waitcnt lgkmcnt(0)
	v_mfma_f32_16x16x32_bf16 v[150:153], v[66:69], v[162:165], 0
	v_mfma_f32_16x16x32_bf16 v[146:149], v[98:101], v[162:165], 0
	v_mfma_f32_16x16x32_bf16 v[126:129], v[66:69], v[170:173], 0
	v_mfma_f32_16x16x32_bf16 v[122:125], v[98:101], v[170:173], 0
	v_mfma_f32_16x16x32_bf16 v[106:109], v[66:69], v[178:181], 0
	v_mfma_f32_16x16x32_bf16 v[102:105], v[98:101], v[178:181], 0
	v_mfma_f32_16x16x32_bf16 v[86:89], v[66:69], v[186:189], 0
	v_mfma_f32_16x16x32_bf16 v[82:85], v[98:101], v[186:189], 0
	v_mfma_f32_16x16x32_bf16 v[150:153], v[78:81], v[166:169], v[150:153]
	v_mfma_f32_16x16x32_bf16 v[146:149], v[118:121], v[166:169], v[146:149]
	v_mfma_f32_16x16x32_bf16 v[126:129], v[78:81], v[174:177], v[126:129]
	v_mfma_f32_16x16x32_bf16 v[122:125], v[118:121], v[174:177], v[122:125]
	v_mfma_f32_16x16x32_bf16 v[106:109], v[78:81], v[182:185], v[106:109]
	v_mfma_f32_16x16x32_bf16 v[102:105], v[118:121], v[182:185], v[102:105]
	v_mfma_f32_16x16x32_bf16 v[86:89], v[78:81], v[190:193], v[86:89]
	v_mfma_f32_16x16x32_bf16 v[82:85], v[118:121], v[190:193], v[82:85]
	v_mfma_f32_16x16x32_bf16 v[134:137], v[138:141], v[162:165], 0
	v_mfma_f32_16x16x32_bf16 v[130:133], v[154:157], v[162:165], 0
	v_mfma_f32_16x16x32_bf16 v[114:117], v[138:141], v[170:173], 0
	v_mfma_f32_16x16x32_bf16 v[110:113], v[154:157], v[170:173], 0
	v_mfma_f32_16x16x32_bf16 v[94:97], v[138:141], v[178:181], 0
	v_mfma_f32_16x16x32_bf16 v[90:93], v[154:157], v[178:181], 0
	v_mfma_f32_16x16x32_bf16 v[74:77], v[138:141], v[186:189], 0
	v_mfma_f32_16x16x32_bf16 v[70:73], v[154:157], v[186:189], 0
	v_mfma_f32_16x16x32_bf16 v[134:137], v[142:145], v[166:169], v[134:137]
	v_mfma_f32_16x16x32_bf16 v[130:133], v[158:161], v[166:169], v[130:133]
	v_mfma_f32_16x16x32_bf16 v[114:117], v[142:145], v[174:177], v[114:117]
	v_mfma_f32_16x16x32_bf16 v[110:113], v[158:161], v[174:177], v[110:113]
	v_mfma_f32_16x16x32_bf16 v[94:97], v[142:145], v[182:185], v[94:97]
	v_mfma_f32_16x16x32_bf16 v[90:93], v[158:161], v[182:185], v[90:93]
	v_mfma_f32_16x16x32_bf16 v[74:77], v[142:145], v[190:193], v[74:77]
	v_mfma_f32_16x16x32_bf16 v[70:73], v[158:161], v[190:193], v[70:73]
	s_barrier
	s_add_i32 s19, s55, s36
	v_lshl_add_u64 v[200:201], s[64:65], 0, v[208:209]
	s_mov_b32 m0, s19
	ds_read_b128 v[162:165], v246 offset:16384
	ds_read_b128 v[166:169], v246 offset:17408
	ds_read_b128 v[170:173], v246 offset:18432
	ds_read_b128 v[174:177], v246 offset:19456
	ds_read_b128 v[178:181], v246 offset:20480
	ds_read_b128 v[182:185], v246 offset:21504
	ds_read_b128 v[186:189], v246 offset:22528
	ds_read_b128 v[190:193], v246 offset:23552
	global_load_lds_dwordx4 v[200:201], off
	s_add_i32 m0, s19, 0x2000
	s_add_u32 s94, s64, 0x40000
	v_lshl_add_u64 v[202:203], s[64:65], 0, v[212:213]
	s_addc_u32 s95, s65, 0
	s_add_i32 s18, s18, s36
	global_load_lds_dwordx4 v[202:203], off
	v_lshl_add_u64 v[224:225], s[94:95], 0, v[208:209]
	s_mov_b32 m0, s18
	v_lshl_add_u64 v[226:227], s[66:67], 0, v[210:211]
	global_load_lds_dwordx4 v[224:225], off
	v_lshl_add_u64 v[224:225], s[94:95], 0, v[212:213]
	s_add_i32 m0, s18, 0x2000
	s_nop 0
	global_load_lds_dwordx4 v[224:225], off
	v_lshl_add_u64 v[224:225], s[66:67], 0, v[206:207]
	s_mov_b32 m0, s37
	s_nop 0
	global_load_lds_dwordx4 v[224:225], off
	s_mov_b32 m0, s61
	s_nop 0
	global_load_lds_dwordx4 v[226:227], off
	s_waitcnt vmcnt(8)
	s_waitcnt lgkmcnt(0)
	s_barrier
	s_waitcnt lgkmcnt(0)
	v_mfma_f32_16x16x32_bf16 v[62:65], v[66:69], v[162:165], 0
	v_mfma_f32_16x16x32_bf16 v[58:61], v[98:101], v[162:165], 0
	v_mfma_f32_16x16x32_bf16 v[46:49], v[66:69], v[170:173], 0
	v_mfma_f32_16x16x32_bf16 v[42:45], v[98:101], v[170:173], 0
	v_mfma_f32_16x16x32_bf16 v[30:33], v[66:69], v[178:181], 0
	v_mfma_f32_16x16x32_bf16 v[26:29], v[98:101], v[178:181], 0
	v_mfma_f32_16x16x32_bf16 v[14:17], v[66:69], v[186:189], 0
	v_mfma_f32_16x16x32_bf16 v[10:13], v[98:101], v[186:189], 0
	v_mfma_f32_16x16x32_bf16 v[62:65], v[78:81], v[166:169], v[62:65]
	v_mfma_f32_16x16x32_bf16 v[58:61], v[118:121], v[166:169], v[58:61]
	v_mfma_f32_16x16x32_bf16 v[46:49], v[78:81], v[174:177], v[46:49]
	v_mfma_f32_16x16x32_bf16 v[42:45], v[118:121], v[174:177], v[42:45]
	v_mfma_f32_16x16x32_bf16 v[30:33], v[78:81], v[182:185], v[30:33]
	v_mfma_f32_16x16x32_bf16 v[26:29], v[118:121], v[182:185], v[26:29]
	v_mfma_f32_16x16x32_bf16 v[14:17], v[78:81], v[190:193], v[14:17]
	v_mfma_f32_16x16x32_bf16 v[10:13], v[118:121], v[190:193], v[10:13]
	v_mfma_f32_16x16x32_bf16 v[54:57], v[138:141], v[162:165], 0
	v_mfma_f32_16x16x32_bf16 v[50:53], v[154:157], v[162:165], 0
	v_mfma_f32_16x16x32_bf16 v[38:41], v[138:141], v[170:173], 0
	v_mfma_f32_16x16x32_bf16 v[34:37], v[154:157], v[170:173], 0
	v_mfma_f32_16x16x32_bf16 v[22:25], v[138:141], v[178:181], 0
	v_mfma_f32_16x16x32_bf16 v[18:21], v[154:157], v[178:181], 0
	v_mfma_f32_16x16x32_bf16 v[6:9], v[138:141], v[186:189], 0
	v_mfma_f32_16x16x32_bf16 v[2:5], v[154:157], v[186:189], 0
	v_mfma_f32_16x16x32_bf16 v[54:57], v[142:145], v[166:169], v[54:57]
	v_mfma_f32_16x16x32_bf16 v[50:53], v[158:161], v[166:169], v[50:53]
	v_mfma_f32_16x16x32_bf16 v[38:41], v[142:145], v[174:177], v[38:41]
	v_mfma_f32_16x16x32_bf16 v[34:37], v[158:161], v[174:177], v[34:37]
	v_mfma_f32_16x16x32_bf16 v[22:25], v[142:145], v[182:185], v[22:25]
	v_mfma_f32_16x16x32_bf16 v[18:21], v[158:161], v[182:185], v[18:21]
	v_mfma_f32_16x16x32_bf16 v[6:9], v[142:145], v[190:193], v[6:9]
	v_mfma_f32_16x16x32_bf16 v[2:5], v[158:161], v[190:193], v[2:5]
	s_barrier
	s_branch .Lp3_win

; #define PG8_STAGE(bufoff, gbase, voff) do { _Pragma("unroll") for (int _i = 0; _i < 2; ++_i) \
;         __builtin_amdgcn_global_load_lds((const unsigned*)((const char*)(gbase) + (voff)[_i]), (LAS unsigned*)(lds + (bufoff) + ldsw + _i * 8192), 16, 0, 0); } while (0)
; #define PG8_LDA(dst, b, h) do { _Pragma("unroll") for (int m = 0; m < 4; ++m) _Pragma("unroll") for (int k = 0; k < 2; ++k) dst[m][k] = *(const LAS bf16x8*)(lds + PG8_SA(b, h) + aoff + m * 2048 + k * 1024); } while (0)
; #define PG8_LDB(dst, b, h) do { _Pragma("unroll") for (int n = 0; n < 2; ++n) _Pragma("unroll") for (int k = 0; k < 2; ++k) dst[n][k] = *(const LAS bf16x8*)(lds + PG8_SB(b, h) + boff + n * 2048 + k * 1024); } while (0)
; #define PG8_MMA(ai, bj, At, Bt) do { __builtin_amdgcn_s_setprio(1); _Pragma("unroll") for (int m = 0; m < 4; ++m) _Pragma("unroll") for (int n = 0; n < 2; ++n) _Pragma("unroll") for (int k = 0; k < 2; ++k) \
;         acc[ai][bj][m][n] = __builtin_amdgcn_mfma_f32_16x16x32_bf16(Bt[n][k], At[m][k], acc[ai][bj][m][n], 0, 0, 0); __builtin_amdgcn_s_setprio(0); } while (0)
; #define PG8_WAIT_V(n) asm volatile("s_waitcnt vmcnt(" #n ")" ::: "memory")
; #define PG8_WAIT_L(n) asm volatile("s_waitcnt lgkmcnt(" #n ")" ::: "memory")
; #define PG8_BAR __builtin_amdgcn_s_barrier()
; #define PG8_SCHED __builtin_amdgcn_sched_barrier(0)
; template <class Epi>
; DI void gemm_phase(LAS unsigned char* lds, const Gemm g, const StaticOrder& S, const Epi& E) {
;     ...
;             PG8_LDB(B0, 1, 0); PG8_LDB(B1, 1, 1); PG8_SCHED; PG8_LDA(At, 1, 0); PG8_STAGE(PG8_SA(0, 1), a2 + hstep, voffA);
;             PG8_WAIT_V(8); PG8_WAIT_L(0); PG8_BAR; PG8_MMA(0, 0, At, B0); PG8_MMA(0, 1, At, B1); PG8_BAR; PG8_SCHED;
.Lp3_win:
	s_add_i32 s18, 0, 0x18000
	s_add_i32 s19, 0, 0x1c000
	v_add_u32_e32 v118, s18, v195
	v_add_u32_e32 v158, s19, v195
	ds_read_b128 v[66:69], v118
	ds_read_b128 v[78:81], v118 offset:1024
	ds_read_b128 v[98:101], v118 offset:2048
	ds_read_b128 v[118:121], v118 offset:3072
	ds_read_b128 v[138:141], v158
	ds_read_b128 v[142:145], v158 offset:1024
	ds_read_b128 v[154:157], v158 offset:2048
	ds_read_b128 v[158:161], v158 offset:3072
	s_add_u32 s66, s66, 0x40000
	s_addc_u32 s67, s67, 0
	s_mov_b32 m0, s68
	v_lshl_add_u64 v[228:229], s[66:67], 0, v[206:207]
	ds_read_b128 v[162:165], v246 offset:32768
	ds_read_b128 v[166:169], v246 offset:33792
	ds_read_b128 v[170:173], v246 offset:34816
	ds_read_b128 v[174:177], v246 offset:35840
	ds_read_b128 v[178:181], v246 offset:36864
	ds_read_b128 v[182:185], v246 offset:37888
	ds_read_b128 v[186:189], v246 offset:38912
	ds_read_b128 v[190:193], v246 offset:39936
	global_load_lds_dwordx4 v[228:229], off
	v_lshl_add_u64 v[228:229], s[66:67], 0, v[210:211]
	s_mov_b32 m0, s69
	s_nop 0
	global_load_lds_dwordx4 v[228:229], off
	s_waitcnt vmcnt(8)
	s_waitcnt lgkmcnt(0)
	s_barrier
	s_waitcnt lgkmcnt(0)
	v_mfma_f32_16x16x32_bf16 v[150:153], v[66:69], v[162:165], v[150:153]
	v_mfma_f32_16x16x32_bf16 v[146:149], v[98:101], v[162:165], v[146:149]
	v_mfma_f32_16x16x32_bf16 v[126:129], v[66:69], v[170:173], v[126:129]
	v_mfma_f32_16x16x32_bf16 v[122:125], v[98:101], v[170:173], v[122:125]
	v_mfma_f32_16x16x32_bf16 v[106:109], v[66:69], v[178:181], v[106:109]
	v_mfma_f32_16x16x32_bf16 v[102:105], v[98:101], v[178:181], v[102:105]
	v_mfma_f32_16x16x32_bf16 v[86:89], v[66:69], v[186:189], v[86:89]
	v_mfma_f32_16x16x32_bf16 v[82:85], v[98:101], v[186:189], v[82:85]
	v_mfma_f32_16x16x32_bf16 v[150:153], v[78:81], v[166:169], v[150:153]
	v_mfma_f32_16x16x32_bf16 v[146:149], v[118:121], v[166:169], v[146:149]
	v_mfma_f32_16x16x32_bf16 v[126:129], v[78:81], v[174:177], v[126:129]
	v_mfma_f32_16x16x32_bf16 v[122:125], v[118:121], v[174:177], v[122:125]
	v_mfma_f32_16x16x32_bf16 v[106:109], v[78:81], v[182:185], v[106:109]
	v_mfma_f32_16x16x32_bf16 v[102:105], v[118:121], v[182:185], v[102:105]
	v_mfma_f32_16x16x32_bf16 v[86:89], v[78:81], v[190:193], v[86:89]
	v_mfma_f32_16x16x32_bf16 v[82:85], v[118:121], v[190:193], v[82:85]
	v_mfma_f32_16x16x32_bf16 v[134:137], v[138:141], v[162:165], v[134:137]
	v_mfma_f32_16x16x32_bf16 v[130:133], v[154:157], v[162:165], v[130:133]
	v_mfma_f32_16x16x32_bf16 v[114:117], v[138:141], v[170:173], v[114:117]
	v_mfma_f32_16x16x32_bf16 v[110:113], v[154:157], v[170:173], v[110:113]
	v_mfma_f32_16x16x32_bf16 v[94:97], v[138:141], v[178:181], v[94:97]
	v_mfma_f32_16x16x32_bf16 v[90:93], v[154:157], v[178:181], v[90:93]
	v_mfma_f32_16x16x32_bf16 v[74:77], v[138:141], v[186:189], v[74:77]
	v_mfma_f32_16x16x32_bf16 v[70:73], v[154:157], v[186:189], v[70:73]
	v_mfma_f32_16x16x32_bf16 v[134:137], v[142:145], v[166:169], v[134:137]
	v_mfma_f32_16x16x32_bf16 v[130:133], v[158:161], v[166:169], v[130:133]
	v_mfma_f32_16x16x32_bf16 v[114:117], v[142:145], v[174:177], v[114:117]
	v_mfma_f32_16x16x32_bf16 v[110:113], v[158:161], v[174:177], v[110:113]
	v_mfma_f32_16x16x32_bf16 v[94:97], v[142:145], v[182:185], v[94:97]
	v_mfma_f32_16x16x32_bf16 v[90:93], v[158:161], v[182:185], v[90:93]
	v_mfma_f32_16x16x32_bf16 v[74:77], v[142:145], v[190:193], v[74:77]
	v_mfma_f32_16x16x32_bf16 v[70:73], v[158:161], v[190:193], v[70:73]
	s_barrier
; #define PG8_STAGE(bufoff, gbase, voff) do { _Pragma("unroll") for (int _i = 0; _i < 2; ++_i) \
;         __builtin_amdgcn_global_load_lds((const unsigned*)((const char*)(gbase) + (voff)[_i]), (LAS unsigned*)(lds + (bufoff) + ldsw + _i * 8192), 16, 0, 0); } while (0)
; #define PG8_LDA(dst, b, h) do { _Pragma("unroll") for (int m = 0; m < 4; ++m) _Pragma("unroll") for (int k = 0; k < 2; ++k) dst[m][k] = *(const LAS bf16x8*)(lds + PG8_SA(b, h) + aoff + m * 2048 + k * 1024); } while (0)
; #define PG8_LDB(dst, b, h) do { _Pragma("unroll") for (int n = 0; n < 2; ++n) _Pragma("unroll") for (int k = 0; k < 2; ++k) dst[n][k] = *(const LAS bf16x8*)(lds + PG8_SB(b, h) + boff + n * 2048 + k * 1024); } while (0)
; #define PG8_WAIT_V(n) asm volatile("s_waitcnt vmcnt(" #n ")" ::: "memory")
; #define PG8_BAR __builtin_amdgcn_s_barrier()
; template <class Epi>
; DI void gemm_phase(LAS unsigned char* lds, const Gemm g, const StaticOrder& S, const Epi& E) {
;     ...
;         for (int t = 0; t < nt; t += 2) {
;             const bool last = (t == nt - 2);
;             const char* a1 = cA + (size_t)(t + 1) * kstep;
;             const char* a2 = last ? nA : cA + (size_t)(t + 2) * kstep; const char* b2 = last ? nB : cB + (size_t)(t + 2) * kstep;
;             const char* a3 = a2 + kstep; const char* b3 = b2 + kstep;
;             PG8_LDB(B0, 0, 0); PG8_LDB(B1, 0, 1); PG8_SCHED; PG8_LDA(At, 0, 0); PG8_STAGE(PG8_SA(1, 1), a1 + hstep, voffA);
;             PG8_WAIT_V(8); PG8_WAIT_L(0); PG8_BAR; PG8_MMA(0, 0, At, B0); PG8_MMA(0, 1, At, B1); PG8_BAR; PG8_SCHED;
;             PG8_LDA(At, 0, 1); PG8_STAGE(PG8_SB(0, 0), b2, voffB); PG8_STAGE(PG8_SB(0, 1), b2 + hstep, voffB); PG8_STAGE(PG8_SA(0, 0), a2, voffA);
;             PG8_WAIT_V(8); PG8_WAIT_L(0); PG8_BAR; PG8_MMA(1, 0, At, B0); PG8_MMA(1, 1, At, B1); PG8_BAR; PG8_SCHED;
;             PG8_LDB(B0, 1, 0); PG8_LDB(B1, 1, 1); PG8_SCHED; PG8_LDA(At, 1, 0); PG8_STAGE(PG8_SA(0, 1), a2 + hstep, voffA);
;             PG8_WAIT_V(8); PG8_WAIT_L(0); PG8_BAR; PG8_MMA(0, 0, At, B0); PG8_MMA(0, 1, At, B1); PG8_BAR; PG8_SCHED;
;             PG8_LDA(At, 1, 1); PG8_STAGE(PG8_SB(1, 0), b3, voffB); PG8_STAGE(PG8_SB(1, 1), b3 + hstep, voffB); PG8_STAGE(PG8_SA(1, 0), a3, voffA);
;             PG8_WAIT_V(8); PG8_WAIT_L(0); PG8_BAR; PG8_MMA(1, 0, At, B0); PG8_MMA(1, 1, At, B1); PG8_BAR; PG8_SCHED;
;         }
;         if (wr == 0) PG8_BAR;
	s_add_i32 s18, s18, s36
	v_lshl_add_u64 v[200:201], v[200:201], 0, s[20:21]
	s_mov_b32 m0, s18
	ds_read_b128 v[162:165], v246 offset:49152
	ds_read_b128 v[166:169], v246 offset:50176
	ds_read_b128 v[170:173], v246 offset:51200
	ds_read_b128 v[174:177], v246 offset:52224
	ds_read_b128 v[178:181], v246 offset:53248
	ds_read_b128 v[182:185], v246 offset:54272
	ds_read_b128 v[186:189], v246 offset:55296
	ds_read_b128 v[190:193], v246 offset:56320
	global_load_lds_dwordx4 v[200:201], off
	s_add_i32 m0, s18, 0x2000
	s_add_u32 s64, s64, 0x40080
	v_lshl_add_u64 v[200:201], v[202:203], 0, s[20:21]
	s_addc_u32 s65, s65, 0
	s_add_i32 s18, s19, s36
	global_load_lds_dwordx4 v[200:201], off
	v_lshl_add_u64 v[200:201], s[64:65], 0, v[208:209]
	s_mov_b32 m0, s18
	s_nop 0
	global_load_lds_dwordx4 v[200:201], off
	v_lshl_add_u64 v[200:201], s[64:65], 0, v[212:213]
	s_add_i32 m0, s18, 0x2000
	s_nop 0
	global_load_lds_dwordx4 v[200:201], off
	v_lshl_add_u64 v[200:201], v[224:225], 0, s[20:21]
	s_mov_b32 m0, s70
	s_nop 0
	global_load_lds_dwordx4 v[200:201], off
	v_lshl_add_u64 v[200:201], v[226:227], 0, s[20:21]
	s_mov_b32 m0, s71
	s_nop 0
	global_load_lds_dwordx4 v[200:201], off
	s_waitcnt vmcnt(8)
	s_waitcnt lgkmcnt(0)
	s_barrier
	s_waitcnt lgkmcnt(0)
	v_mfma_f32_16x16x32_bf16 v[62:65], v[66:69], v[162:165], v[62:65]
	v_mfma_f32_16x16x32_bf16 v[58:61], v[98:101], v[162:165], v[58:61]
	v_mfma_f32_16x16x32_bf16 v[46:49], v[66:69], v[170:173], v[46:49]
	v_mfma_f32_16x16x32_bf16 v[42:45], v[98:101], v[170:173], v[42:45]
	v_mfma_f32_16x16x32_bf16 v[30:33], v[66:69], v[178:181], v[30:33]
	v_mfma_f32_16x16x32_bf16 v[26:29], v[98:101], v[178:181], v[26:29]
	v_mfma_f32_16x16x32_bf16 v[14:17], v[66:69], v[186:189], v[14:17]
	v_mfma_f32_16x16x32_bf16 v[10:13], v[98:101], v[186:189], v[10:13]
	v_mfma_f32_16x16x32_bf16 v[62:65], v[78:81], v[166:169], v[62:65]
	v_mfma_f32_16x16x32_bf16 v[58:61], v[118:121], v[166:169], v[58:61]
	v_mfma_f32_16x16x32_bf16 v[46:49], v[78:81], v[174:177], v[46:49]
	v_mfma_f32_16x16x32_bf16 v[42:45], v[118:121], v[174:177], v[42:45]
	v_mfma_f32_16x16x32_bf16 v[30:33], v[78:81], v[182:185], v[30:33]
	v_mfma_f32_16x16x32_bf16 v[26:29], v[118:121], v[182:185], v[26:29]
	v_mfma_f32_16x16x32_bf16 v[14:17], v[78:81], v[190:193], v[14:17]
	v_mfma_f32_16x16x32_bf16 v[10:13], v[118:121], v[190:193], v[10:13]
	v_mfma_f32_16x16x32_bf16 v[54:57], v[138:141], v[162:165], v[54:57]
	v_mfma_f32_16x16x32_bf16 v[50:53], v[154:157], v[162:165], v[50:53]
	v_mfma_f32_16x16x32_bf16 v[38:41], v[138:141], v[170:173], v[38:41]
	v_mfma_f32_16x16x32_bf16 v[34:37], v[154:157], v[170:173], v[34:37]
	v_mfma_f32_16x16x32_bf16 v[22:25], v[138:141], v[178:181], v[22:25]
	v_mfma_f32_16x16x32_bf16 v[18:21], v[154:157], v[178:181], v[18:21]
	v_mfma_f32_16x16x32_bf16 v[6:9], v[138:141], v[186:189], v[6:9]
	v_mfma_f32_16x16x32_bf16 v[2:5], v[154:157], v[186:189], v[2:5]
	v_mfma_f32_16x16x32_bf16 v[54:57], v[142:145], v[166:169], v[54:57]
	v_mfma_f32_16x16x32_bf16 v[50:53], v[158:161], v[166:169], v[50:53]
	v_mfma_f32_16x16x32_bf16 v[38:41], v[142:145], v[174:177], v[38:41]
	v_mfma_f32_16x16x32_bf16 v[34:37], v[158:161], v[174:177], v[34:37]
	v_mfma_f32_16x16x32_bf16 v[22:25], v[142:145], v[182:185], v[22:25]
	v_mfma_f32_16x16x32_bf16 v[18:21], v[158:161], v[182:185], v[18:21]
	v_mfma_f32_16x16x32_bf16 v[6:9], v[142:145], v[190:193], v[6:9]
	v_mfma_f32_16x16x32_bf16 v[2:5], v[158:161], v[190:193], v[2:5]
	s_barrier
	s_add_i32 s53, s53, 2
	s_add_u32 s42, s42, 0x100
	s_addc_u32 s43, s43, 0
	s_add_u32 s62, s62, 0x100
	s_addc_u32 s63, s63, 0
	s_cmp_gt_u32 s53, 13
	s_cbranch_scc0 .LBB0_92
	s_setprio 0
	s_and_b64 vcc, exec, s[50:51]
	s_cbranch_vccz .LBB0_95
	s_barrier

; template <class Epi>
; DI void gemm_phase(LAS unsigned char* lds, const Gemm g, const StaticOrder& S, const Epi& E) {
;     ...
;         const bool has_next = S.next(ui + 1, nxt);
;         const char* nA = has_next ? (const char*)g.A + (size_t)nxt.pm * tstep : cA; const char* nB = has_next ? (const char*)g.Bt + (size_t)nxt.pn * tstep : cB;
;     ...
;         for (int a = 0; a < 2; ++a)
; #pragma unroll
;             for (int b = 0; b < 2; ++b)
; #pragma unroll
;                 for (int m = 0; m < 4; ++m)
; #pragma unroll
;                     for (int n = 0; n < 2; ++n) acc[a][b][m][n] = (f32x4){0.f, 0.f, 0.f, 0.f};
.LBB0_700:
	s_ashr_i32 s49, s48, 31
	s_lshl_b64 s[18:19], s[48:49], 19
	s_add_u32 s50, s25, s18
	s_addc_u32 s51, s30, s19
	s_and_b64 s[18:19], s[4:5], exec
	s_cselect_b32 s22, s51, s59
	s_cselect_b32 s23, s50, s58
	s_ashr_i32 s47, s46, 31
	s_lshl_b64 s[18:19], s[46:47], 19
	s_add_u32 s52, s31, s18
	s_addc_u32 s53, s36, s19
	s_and_b64 s[18:19], s[4:5], exec
	s_cselect_b32 s42, s53, s57
	s_cselect_b32 s43, s52, s56
	s_add_u32 s47, s56, 0x100
	s_addc_u32 s49, s57, 0
	s_add_u32 s56, s58, 0x40080
	s_addc_u32 s57, s59, 0
	s_mov_b32 s68, -2
	v_readfirstlane_b32 s101, v242
	s_nop 3
	s_lshr_b32 s101, s101, 8
	s_cmp_eq_u32 s101, 0
	s_cbranch_scc0 .Lsp_1
	s_setprio 1
; #define PG8_STAGE(bufoff, gbase, voff) do { _Pragma("unroll") for (int _i = 0; _i < 2; ++_i) \
;         __builtin_amdgcn_global_load_lds((const unsigned*)((const char*)(gbase) + (voff)[_i]), (LAS unsigned*)(lds + (bufoff) + ldsw + _i * 8192), 16, 0, 0); } while (0)
; #define PG8_LDA(dst, b, h) do { _Pragma("unroll") for (int m = 0; m < 4; ++m) _Pragma("unroll") for (int k = 0; k < 2; ++k) dst[m][k] = *(const LAS bf16x8*)(lds + PG8_SA(b, h) + aoff + m * 2048 + k * 1024); } while (0)
; #define PG8_LDB(dst, b, h) do { _Pragma("unroll") for (int n = 0; n < 2; ++n) _Pragma("unroll") for (int k = 0; k < 2; ++k) dst[n][k] = *(const LAS bf16x8*)(lds + PG8_SB(b, h) + boff + n * 2048 + k * 1024); } while (0)
; #define PG8_MMA(ai, bj, At, Bt) do { __builtin_amdgcn_s_setprio(1); _Pragma("unroll") for (int m = 0; m < 4; ++m) _Pragma("unroll") for (int n = 0; n < 2; ++n) _Pragma("unroll") for (int k = 0; k < 2; ++k) \
;         acc[ai][bj][m][n] = __builtin_amdgcn_mfma_f32_16x16x32_bf16(Bt[n][k], At[m][k], acc[ai][bj][m][n], 0, 0, 0); __builtin_amdgcn_s_setprio(0); } while (0)
; #define PG8_WAIT_V(n) asm volatile("s_waitcnt vmcnt(" #n ")" ::: "memory")
; #define PG8_WAIT_L(n) asm volatile("s_waitcnt lgkmcnt(" #n ")" ::: "memory")
; #define PG8_BAR __builtin_amdgcn_s_barrier()
; #define PG8_SCHED __builtin_amdgcn_sched_barrier(0)
; template <class Epi>
; DI void gemm_phase(LAS unsigned char* lds, const Gemm g, const StaticOrder& S, const Epi& E) {
;     ...
;             PG8_LDB(B0, 0, 0); PG8_LDB(B1, 0, 1); PG8_SCHED; PG8_LDA(At, 0, 0); PG8_STAGE(PG8_SA(1, 1), a1 + hstep, voffA);
;             PG8_WAIT_V(8); PG8_WAIT_L(0); PG8_BAR; PG8_MMA(0, 0, At, B0); PG8_MMA(0, 1, At, B1); PG8_BAR; PG8_SCHED;
;             PG8_LDA(At, 0, 1); PG8_STAGE(PG8_SB(0, 0), b2, voffB); PG8_STAGE(PG8_SB(0, 1), b2 + hstep, voffB); PG8_STAGE(PG8_SA(0, 0), a2, voffA);
;             PG8_WAIT_V(8); PG8_WAIT_L(0); PG8_BAR; PG8_MMA(1, 0, At, B0); PG8_MMA(1, 1, At, B1); PG8_BAR; PG8_SCHED;
.Lsp_1:
	s_add_u32 s18, s56, 0xfffc0080
	s_addc_u32 s19, s57, -1
	s_add_i32 s69, 0, 0x10000
	s_cmp_eq_u32 s68, 12
	s_cselect_b32 s61, s22, s19
	s_cselect_b32 s60, s23, s18
	v_add_u32_e32 v122, s69, v184
	s_cselect_b32 s59, s42, s49
	s_cselect_b32 s58, s43, s47
	s_add_i32 s70, 0, 0x14000
	ds_read_b128 v[102:105], v122
	ds_read_b128 v[132:135], v122 offset:1024
	ds_read_b128 v[140:143], v122 offset:2048
	ds_read_b128 v[144:147], v122 offset:3072
	v_add_u32_e32 v122, s70, v184
	ds_read_b128 v[148:151], v122
	ds_read_b128 v[166:169], v122 offset:1024
	ds_read_b128 v[170:173], v122 offset:2048
	ds_read_b128 v[174:177], v122 offset:3072
	v_lshl_add_u64 v[122:123], s[56:57], 0, v[164:165]
	s_add_i32 m0, s55, 0xc000
	ds_read_b128 v[178:181], v186
	ds_read_b128 v[188:191], v186 offset:1024
	ds_read_b128 v[200:203], v186 offset:2048
	ds_read_b128 v[206:209], v186 offset:3072
	ds_read_b128 v[210:213], v186 offset:4096
	ds_read_b128 v[214:217], v186 offset:5120
	ds_read_b128 v[218:221], v186 offset:6144
	ds_read_b128 v[222:225], v186 offset:7168
	global_load_lds_dwordx4 v[122:123], off
	v_lshl_add_u64 v[122:123], s[56:57], 0, v[162:163]
	s_add_i32 m0, s55, 0xe000
	s_nop 0
	global_load_lds_dwordx4 v[122:123], off
	s_waitcnt vmcnt(8)
	s_waitcnt lgkmcnt(0)
	s_barrier
	s_waitcnt lgkmcnt(0)
	v_mfma_f32_16x16x32_bf16 v[136:139], v[102:105], v[178:181], 0
	v_mfma_f32_16x16x32_bf16 v[128:131], v[140:143], v[178:181], 0
	v_mfma_f32_16x16x32_bf16 v[118:121], v[102:105], v[200:203], 0
	v_mfma_f32_16x16x32_bf16 v[110:113], v[140:143], v[200:203], 0
	v_mfma_f32_16x16x32_bf16 v[98:101], v[102:105], v[210:213], 0
	v_mfma_f32_16x16x32_bf16 v[90:93], v[140:143], v[210:213], 0
	v_mfma_f32_16x16x32_bf16 v[78:81], v[102:105], v[218:221], 0
	v_mfma_f32_16x16x32_bf16 v[70:73], v[140:143], v[218:221], 0
	v_mfma_f32_16x16x32_bf16 v[136:139], v[132:135], v[188:191], v[136:139]
	v_mfma_f32_16x16x32_bf16 v[128:131], v[144:147], v[188:191], v[128:131]
	v_mfma_f32_16x16x32_bf16 v[118:121], v[132:135], v[206:209], v[118:121]
	v_mfma_f32_16x16x32_bf16 v[110:113], v[144:147], v[206:209], v[110:113]
	v_mfma_f32_16x16x32_bf16 v[98:101], v[132:135], v[214:217], v[98:101]
	v_mfma_f32_16x16x32_bf16 v[90:93], v[144:147], v[214:217], v[90:93]
	v_mfma_f32_16x16x32_bf16 v[78:81], v[132:135], v[222:225], v[78:81]
	v_mfma_f32_16x16x32_bf16 v[70:73], v[144:147], v[222:225], v[70:73]
	v_mfma_f32_16x16x32_bf16 v[82:85], v[148:151], v[178:181], 0
	v_mfma_f32_16x16x32_bf16 v[122:125], v[170:173], v[178:181], 0
	v_mfma_f32_16x16x32_bf16 v[114:117], v[148:151], v[200:203], 0
	v_mfma_f32_16x16x32_bf16 v[106:109], v[170:173], v[200:203], 0
	v_mfma_f32_16x16x32_bf16 v[94:97], v[148:151], v[210:213], 0
	v_mfma_f32_16x16x32_bf16 v[86:89], v[170:173], v[210:213], 0
	v_mfma_f32_16x16x32_bf16 v[74:77], v[148:151], v[218:221], 0
	v_mfma_f32_16x16x32_bf16 v[66:69], v[170:173], v[218:221], 0
	v_mfma_f32_16x16x32_bf16 v[82:85], v[166:169], v[188:191], v[82:85]
	v_mfma_f32_16x16x32_bf16 v[122:125], v[174:177], v[188:191], v[122:125]
	v_mfma_f32_16x16x32_bf16 v[114:117], v[166:169], v[206:209], v[114:117]
	v_mfma_f32_16x16x32_bf16 v[106:109], v[174:177], v[206:209], v[106:109]
	v_mfma_f32_16x16x32_bf16 v[94:97], v[166:169], v[214:217], v[94:97]
	v_mfma_f32_16x16x32_bf16 v[86:89], v[174:177], v[214:217], v[86:89]
	v_mfma_f32_16x16x32_bf16 v[74:77], v[166:169], v[222:225], v[74:77]
	v_mfma_f32_16x16x32_bf16 v[66:69], v[174:177], v[222:225], v[66:69]
	s_barrier
	s_add_i32 s18, s69, s37
	v_lshl_add_u64 v[182:183], s[58:59], 0, v[156:157]
	s_mov_b32 m0, s18
	ds_read_b128 v[178:181], v186 offset:16384
	ds_read_b128 v[188:191], v186 offset:17408
	ds_read_b128 v[200:203], v186 offset:18432
	ds_read_b128 v[206:209], v186 offset:19456
	ds_read_b128 v[210:213], v186 offset:20480
	ds_read_b128 v[214:217], v186 offset:21504
	ds_read_b128 v[218:221], v186 offset:22528
	ds_read_b128 v[222:225], v186 offset:23552
	global_load_lds_dwordx4 v[182:183], off
	s_add_i32 m0, s18, 0x2000
	s_add_u32 s18, s58, 0x40000
	v_lshl_add_u64 v[192:193], s[58:59], 0, v[152:153]
	s_addc_u32 s19, s59, 0
	s_add_i32 s69, s70, s37
	global_load_lds_dwordx4 v[192:193], off
	v_lshl_add_u64 v[126:127], s[18:19], 0, v[156:157]
	s_mov_b32 m0, s69
	v_lshl_add_u64 v[204:205], s[60:61], 0, v[158:159]
	global_load_lds_dwordx4 v[126:127], off
	v_lshl_add_u64 v[126:127], s[18:19], 0, v[152:153]
	s_add_i32 m0, s69, 0x2000
	v_lshl_add_u64 v[226:227], s[60:61], 0, v[154:155]
	global_load_lds_dwordx4 v[126:127], off
	s_mov_b32 m0, s55
	s_nop 0
	global_load_lds_dwordx4 v[204:205], off
	s_mov_b32 m0, s63
	s_nop 0
	global_load_lds_dwordx4 v[226:227], off
	s_waitcnt vmcnt(8)
	s_waitcnt lgkmcnt(0)
	s_barrier
	s_waitcnt lgkmcnt(0)
	v_mfma_f32_16x16x32_bf16 v[62:65], v[102:105], v[178:181], 0
	v_mfma_f32_16x16x32_bf16 v[54:57], v[140:143], v[178:181], 0
	v_mfma_f32_16x16x32_bf16 v[46:49], v[102:105], v[200:203], 0
	v_mfma_f32_16x16x32_bf16 v[38:41], v[140:143], v[200:203], 0
	v_mfma_f32_16x16x32_bf16 v[30:33], v[102:105], v[210:213], 0
	v_mfma_f32_16x16x32_bf16 v[22:25], v[140:143], v[210:213], 0
	v_mfma_f32_16x16x32_bf16 v[14:17], v[102:105], v[218:221], 0
	v_mfma_f32_16x16x32_bf16 v[6:9], v[140:143], v[218:221], 0
	v_mfma_f32_16x16x32_bf16 v[62:65], v[132:135], v[188:191], v[62:65]
	v_mfma_f32_16x16x32_bf16 v[54:57], v[144:147], v[188:191], v[54:57]
	v_mfma_f32_16x16x32_bf16 v[46:49], v[132:135], v[206:209], v[46:49]
	v_mfma_f32_16x16x32_bf16 v[38:41], v[144:147], v[206:209], v[38:41]
	v_mfma_f32_16x16x32_bf16 v[30:33], v[132:135], v[214:217], v[30:33]
	v_mfma_f32_16x16x32_bf16 v[22:25], v[144:147], v[214:217], v[22:25]
	v_mfma_f32_16x16x32_bf16 v[14:17], v[132:135], v[222:225], v[14:17]
	v_mfma_f32_16x16x32_bf16 v[6:9], v[144:147], v[222:225], v[6:9]
	v_mfma_f32_16x16x32_bf16 v[58:61], v[148:151], v[178:181], 0
	v_mfma_f32_16x16x32_bf16 v[50:53], v[170:173], v[178:181], 0
	v_mfma_f32_16x16x32_bf16 v[42:45], v[148:151], v[200:203], 0
	v_mfma_f32_16x16x32_bf16 v[34:37], v[170:173], v[200:203], 0
	v_mfma_f32_16x16x32_bf16 v[26:29], v[148:151], v[210:213], 0
	v_mfma_f32_16x16x32_bf16 v[18:21], v[170:173], v[210:213], 0
	v_mfma_f32_16x16x32_bf16 v[10:13], v[148:151], v[218:221], 0
	v_mfma_f32_16x16x32_bf16 v[2:5], v[170:173], v[218:221], 0
	v_mfma_f32_16x16x32_bf16 v[58:61], v[166:169], v[188:191], v[58:61]
	v_mfma_f32_16x16x32_bf16 v[50:53], v[174:177], v[188:191], v[50:53]
	v_mfma_f32_16x16x32_bf16 v[42:45], v[166:169], v[206:209], v[42:45]
	v_mfma_f32_16x16x32_bf16 v[34:37], v[174:177], v[206:209], v[34:37]
	v_mfma_f32_16x16x32_bf16 v[26:29], v[166:169], v[214:217], v[26:29]
	v_mfma_f32_16x16x32_bf16 v[18:21], v[174:177], v[214:217], v[18:21]
	v_mfma_f32_16x16x32_bf16 v[10:13], v[166:169], v[222:225], v[10:13]
	v_mfma_f32_16x16x32_bf16 v[2:5], v[174:177], v[222:225], v[2:5]
	s_barrier
	s_branch .Lp3_gu

; #define PG8_STAGE(bufoff, gbase, voff) do { _Pragma("unroll") for (int _i = 0; _i < 2; ++_i) \
;         __builtin_amdgcn_global_load_lds((const unsigned*)((const char*)(gbase) + (voff)[_i]), (LAS unsigned*)(lds + (bufoff) + ldsw + _i * 8192), 16, 0, 0); } while (0)
; #define PG8_LDA(dst, b, h) do { _Pragma("unroll") for (int m = 0; m < 4; ++m) _Pragma("unroll") for (int k = 0; k < 2; ++k) dst[m][k] = *(const LAS bf16x8*)(lds + PG8_SA(b, h) + aoff + m * 2048 + k * 1024); } while (0)
; #define PG8_LDB(dst, b, h) do { _Pragma("unroll") for (int n = 0; n < 2; ++n) _Pragma("unroll") for (int k = 0; k < 2; ++k) dst[n][k] = *(const LAS bf16x8*)(lds + PG8_SB(b, h) + boff + n * 2048 + k * 1024); } while (0)
; #define PG8_MMA(ai, bj, At, Bt) do { __builtin_amdgcn_s_setprio(1); _Pragma("unroll") for (int m = 0; m < 4; ++m) _Pragma("unroll") for (int n = 0; n < 2; ++n) _Pragma("unroll") for (int k = 0; k < 2; ++k) \
;         acc[ai][bj][m][n] = __builtin_amdgcn_mfma_f32_16x16x32_bf16(Bt[n][k], At[m][k], acc[ai][bj][m][n], 0, 0, 0); __builtin_amdgcn_s_setprio(0); } while (0)
; #define PG8_WAIT_V(n) asm volatile("s_waitcnt vmcnt(" #n ")" ::: "memory")
; #define PG8_WAIT_L(n) asm volatile("s_waitcnt lgkmcnt(" #n ")" ::: "memory")
; #define PG8_BAR __builtin_amdgcn_s_barrier()
; #define PG8_SCHED __builtin_amdgcn_sched_barrier(0)
; template <class Epi>
; DI void gemm_phase(LAS unsigned char* lds, const Gemm g, const StaticOrder& S, const Epi& E) {
;     ...
;             PG8_LDB(B0, 1, 0); PG8_LDB(B1, 1, 1); PG8_SCHED; PG8_LDA(At, 1, 0); PG8_STAGE(PG8_SA(0, 1), a2 + hstep, voffA);
;             PG8_WAIT_V(8); PG8_WAIT_L(0); PG8_BAR; PG8_MMA(0, 0, At, B0); PG8_MMA(0, 1, At, B1); PG8_BAR; PG8_SCHED;
.Lp3_gu:
	s_add_i32 s69, 0, 0x18000
	v_add_u32_e32 v126, s69, v184
	s_add_i32 s70, 0, 0x1c000
	ds_read_b128 v[102:105], v126
	ds_read_b128 v[132:135], v126 offset:1024
	ds_read_b128 v[140:143], v126 offset:2048
	ds_read_b128 v[144:147], v126 offset:3072
	v_add_u32_e32 v126, s70, v184
	ds_read_b128 v[148:151], v126
	ds_read_b128 v[166:169], v126 offset:1024
	ds_read_b128 v[170:173], v126 offset:2048
	ds_read_b128 v[174:177], v126 offset:3072
	s_add_u32 s18, s60, 0x40000
	s_addc_u32 s19, s61, 0
	s_mov_b32 m0, s64
	v_lshl_add_u64 v[126:127], s[18:19], 0, v[158:159]
	ds_read_b128 v[178:181], v186 offset:32768
	ds_read_b128 v[188:191], v186 offset:33792
	ds_read_b128 v[200:203], v186 offset:34816
	ds_read_b128 v[206:209], v186 offset:35840
	ds_read_b128 v[210:213], v186 offset:36864
	ds_read_b128 v[214:217], v186 offset:37888
	ds_read_b128 v[218:221], v186 offset:38912
	ds_read_b128 v[222:225], v186 offset:39936
	global_load_lds_dwordx4 v[126:127], off
	v_lshl_add_u64 v[126:127], s[18:19], 0, v[154:155]
	s_mov_b32 m0, s65
	s_nop 0
	global_load_lds_dwordx4 v[126:127], off
	s_waitcnt vmcnt(8)
	s_waitcnt lgkmcnt(0)
	s_barrier
	s_waitcnt lgkmcnt(0)
	v_mfma_f32_16x16x32_bf16 v[136:139], v[102:105], v[178:181], v[136:139]
	v_mfma_f32_16x16x32_bf16 v[126:129], v[140:143], v[178:181], v[128:131]
	v_mfma_f32_16x16x32_bf16 v[118:121], v[102:105], v[200:203], v[118:121]
	v_mfma_f32_16x16x32_bf16 v[110:113], v[140:143], v[200:203], v[110:113]
	v_mfma_f32_16x16x32_bf16 v[98:101], v[102:105], v[210:213], v[98:101]
	v_mfma_f32_16x16x32_bf16 v[90:93], v[140:143], v[210:213], v[90:93]
	v_mfma_f32_16x16x32_bf16 v[78:81], v[102:105], v[218:221], v[78:81]
	v_mfma_f32_16x16x32_bf16 v[70:73], v[140:143], v[218:221], v[70:73]
	v_mfma_f32_16x16x32_bf16 v[136:139], v[132:135], v[188:191], v[136:139]
	v_mfma_f32_16x16x32_bf16 v[128:131], v[144:147], v[188:191], v[126:129]
	v_mfma_f32_16x16x32_bf16 v[118:121], v[132:135], v[206:209], v[118:121]
	v_mfma_f32_16x16x32_bf16 v[110:113], v[144:147], v[206:209], v[110:113]
	v_mfma_f32_16x16x32_bf16 v[98:101], v[132:135], v[214:217], v[98:101]
	v_mfma_f32_16x16x32_bf16 v[90:93], v[144:147], v[214:217], v[90:93]
	v_mfma_f32_16x16x32_bf16 v[78:81], v[132:135], v[222:225], v[78:81]
	v_mfma_f32_16x16x32_bf16 v[70:73], v[144:147], v[222:225], v[70:73]
	v_mfma_f32_16x16x32_bf16 v[82:85], v[148:151], v[178:181], v[82:85]
	v_mfma_f32_16x16x32_bf16 v[122:125], v[170:173], v[178:181], v[122:125]
	v_mfma_f32_16x16x32_bf16 v[114:117], v[148:151], v[200:203], v[114:117]
	v_mfma_f32_16x16x32_bf16 v[106:109], v[170:173], v[200:203], v[106:109]
	v_mfma_f32_16x16x32_bf16 v[94:97], v[148:151], v[210:213], v[94:97]
	v_mfma_f32_16x16x32_bf16 v[86:89], v[170:173], v[210:213], v[86:89]
	v_mfma_f32_16x16x32_bf16 v[74:77], v[148:151], v[218:221], v[74:77]
	v_mfma_f32_16x16x32_bf16 v[66:69], v[170:173], v[218:221], v[66:69]
	v_mfma_f32_16x16x32_bf16 v[82:85], v[166:169], v[188:191], v[82:85]
	v_mfma_f32_16x16x32_bf16 v[124:127], v[174:177], v[188:191], v[122:125]
	v_mfma_f32_16x16x32_bf16 v[114:117], v[166:169], v[206:209], v[114:117]
	v_mfma_f32_16x16x32_bf16 v[106:109], v[174:177], v[206:209], v[106:109]
	v_mfma_f32_16x16x32_bf16 v[94:97], v[166:169], v[214:217], v[94:97]
	v_mfma_f32_16x16x32_bf16 v[86:89], v[174:177], v[214:217], v[86:89]
	v_mfma_f32_16x16x32_bf16 v[74:77], v[166:169], v[222:225], v[74:77]
	v_mfma_f32_16x16x32_bf16 v[66:69], v[174:177], v[222:225], v[66:69]
	s_barrier
; #define PG8_STAGE(bufoff, gbase, voff) do { _Pragma("unroll") for (int _i = 0; _i < 2; ++_i) \
;         __builtin_amdgcn_global_load_lds((const unsigned*)((const char*)(gbase) + (voff)[_i]), (LAS unsigned*)(lds + (bufoff) + ldsw + _i * 8192), 16, 0, 0); } while (0)
; #define PG8_LDA(dst, b, h) do { _Pragma("unroll") for (int m = 0; m < 4; ++m) _Pragma("unroll") for (int k = 0; k < 2; ++k) dst[m][k] = *(const LAS bf16x8*)(lds + PG8_SA(b, h) + aoff + m * 2048 + k * 1024); } while (0)
; #define PG8_MMA(ai, bj, At, Bt) do { __builtin_amdgcn_s_setprio(1); _Pragma("unroll") for (int m = 0; m < 4; ++m) _Pragma("unroll") for (int n = 0; n < 2; ++n) _Pragma("unroll") for (int k = 0; k < 2; ++k) \
;         acc[ai][bj][m][n] = __builtin_amdgcn_mfma_f32_16x16x32_bf16(Bt[n][k], At[m][k], acc[ai][bj][m][n], 0, 0, 0); __builtin_amdgcn_s_setprio(0); } while (0)
; #define PG8_WAIT_V(n) asm volatile("s_waitcnt vmcnt(" #n ")" ::: "memory")
; #define PG8_WAIT_L(n) asm volatile("s_waitcnt lgkmcnt(" #n ")" ::: "memory")
; #define PG8_BAR __builtin_amdgcn_s_barrier()
; #define PG8_SCHED __builtin_amdgcn_sched_barrier(0)
; template <class Epi>
; DI void gemm_phase(LAS unsigned char* lds, const Gemm g, const StaticOrder& S, const Epi& E) {
;     ...
;             PG8_LDA(At, 1, 1); PG8_STAGE(PG8_SB(1, 0), b3, voffB); PG8_STAGE(PG8_SB(1, 1), b3 + hstep, voffB); PG8_STAGE(PG8_SA(1, 0), a3, voffA);
;             PG8_WAIT_V(8); PG8_WAIT_L(0); PG8_BAR; PG8_MMA(1, 0, At, B0); PG8_MMA(1, 1, At, B1); PG8_BAR; PG8_SCHED;
;         }
;         if (wr == 0) PG8_BAR;
	s_add_i32 s18, s69, s37
	v_lshl_add_u64 v[122:123], v[182:183], 0, s[20:21]
	s_mov_b32 m0, s18
	ds_read_b128 v[178:181], v186 offset:49152
	ds_read_b128 v[188:191], v186 offset:50176
	ds_read_b128 v[200:203], v186 offset:51200
	ds_read_b128 v[206:209], v186 offset:52224
	ds_read_b128 v[210:213], v186 offset:53248
	ds_read_b128 v[214:217], v186 offset:54272
	ds_read_b128 v[218:221], v186 offset:55296
	ds_read_b128 v[222:225], v186 offset:56320
	global_load_lds_dwordx4 v[122:123], off
	s_add_i32 m0, s18, 0x2000
	s_add_u32 s18, s58, 0x40080
	v_lshl_add_u64 v[122:123], v[192:193], 0, s[20:21]
	s_addc_u32 s19, s59, 0
	s_add_i32 s58, s70, s37
	global_load_lds_dwordx4 v[122:123], off
	v_lshl_add_u64 v[122:123], s[18:19], 0, v[156:157]
	s_mov_b32 m0, s58
	s_nop 0
	global_load_lds_dwordx4 v[122:123], off
	v_lshl_add_u64 v[122:123], s[18:19], 0, v[152:153]
	s_add_i32 m0, s58, 0x2000
	s_nop 0
	global_load_lds_dwordx4 v[122:123], off
	v_lshl_add_u64 v[122:123], v[204:205], 0, s[20:21]
	s_mov_b32 m0, s66
	s_nop 0
	global_load_lds_dwordx4 v[122:123], off
	v_lshl_add_u64 v[122:123], v[226:227], 0, s[20:21]
	s_mov_b32 m0, s67
	s_nop 0
	global_load_lds_dwordx4 v[122:123], off
	s_waitcnt vmcnt(8)
	s_waitcnt lgkmcnt(0)
	s_barrier
	s_waitcnt lgkmcnt(0)
	v_mfma_f32_16x16x32_bf16 v[62:65], v[102:105], v[178:181], v[62:65]
	v_mfma_f32_16x16x32_bf16 v[54:57], v[140:143], v[178:181], v[54:57]
	v_mfma_f32_16x16x32_bf16 v[46:49], v[102:105], v[200:203], v[46:49]
	v_mfma_f32_16x16x32_bf16 v[38:41], v[140:143], v[200:203], v[38:41]
	v_mfma_f32_16x16x32_bf16 v[30:33], v[102:105], v[210:213], v[30:33]
	v_mfma_f32_16x16x32_bf16 v[22:25], v[140:143], v[210:213], v[22:25]
	v_mfma_f32_16x16x32_bf16 v[14:17], v[102:105], v[218:221], v[14:17]
	v_mfma_f32_16x16x32_bf16 v[6:9], v[140:143], v[218:221], v[6:9]
	v_mfma_f32_16x16x32_bf16 v[62:65], v[132:135], v[188:191], v[62:65]
	v_mfma_f32_16x16x32_bf16 v[54:57], v[144:147], v[188:191], v[54:57]
	v_mfma_f32_16x16x32_bf16 v[46:49], v[132:135], v[206:209], v[46:49]
	v_mfma_f32_16x16x32_bf16 v[38:41], v[144:147], v[206:209], v[38:41]
	v_mfma_f32_16x16x32_bf16 v[30:33], v[132:135], v[214:217], v[30:33]
	v_mfma_f32_16x16x32_bf16 v[22:25], v[144:147], v[214:217], v[22:25]
	v_mfma_f32_16x16x32_bf16 v[14:17], v[132:135], v[222:225], v[14:17]
	v_mfma_f32_16x16x32_bf16 v[6:9], v[144:147], v[222:225], v[6:9]
	v_mfma_f32_16x16x32_bf16 v[58:61], v[148:151], v[178:181], v[58:61]
	v_mfma_f32_16x16x32_bf16 v[50:53], v[170:173], v[178:181], v[50:53]
	v_mfma_f32_16x16x32_bf16 v[42:45], v[148:151], v[200:203], v[42:45]
	v_mfma_f32_16x16x32_bf16 v[34:37], v[170:173], v[200:203], v[34:37]
	v_mfma_f32_16x16x32_bf16 v[26:29], v[148:151], v[210:213], v[26:29]
	v_mfma_f32_16x16x32_bf16 v[18:21], v[170:173], v[210:213], v[18:21]
	v_mfma_f32_16x16x32_bf16 v[10:13], v[148:151], v[218:221], v[10:13]
	v_mfma_f32_16x16x32_bf16 v[2:5], v[170:173], v[218:221], v[2:5]
	v_mfma_f32_16x16x32_bf16 v[58:61], v[166:169], v[188:191], v[58:61]
	v_mfma_f32_16x16x32_bf16 v[50:53], v[174:177], v[188:191], v[50:53]
	v_mfma_f32_16x16x32_bf16 v[42:45], v[166:169], v[206:209], v[42:45]
	v_mfma_f32_16x16x32_bf16 v[34:37], v[174:177], v[206:209], v[34:37]
	v_mfma_f32_16x16x32_bf16 v[26:29], v[166:169], v[214:217], v[26:29]
	v_mfma_f32_16x16x32_bf16 v[18:21], v[174:177], v[214:217], v[18:21]
	v_mfma_f32_16x16x32_bf16 v[10:13], v[166:169], v[222:225], v[10:13]
	v_mfma_f32_16x16x32_bf16 v[2:5], v[174:177], v[222:225], v[2:5]
	s_barrier
	s_add_i32 s68, s68, 2
	s_add_u32 s47, s47, 0x100
	s_addc_u32 s49, s49, 0
	s_add_u32 s56, s56, 0x100
	s_addc_u32 s57, s57, 0
	s_cmp_gt_u32 s68, 13
	s_cbranch_scc0 .LBB0_701
	s_setprio 0
	s_and_b64 vcc, exec, s[44:45]
	s_cbranch_vccz .LBB0_704
	s_barrier

; #define PG8_STAGE(bufoff, gbase, voff) do { _Pragma("unroll") for (int _i = 0; _i < 2; ++_i) \
;         __builtin_amdgcn_global_load_lds((const unsigned*)((const char*)(gbase) + (voff)[_i]), (LAS unsigned*)(lds + (bufoff) + ldsw + _i * 8192), 16, 0, 0); } while (0)
; #define PG8_LDA(dst, b, h) do { _Pragma("unroll") for (int m = 0; m < 4; ++m) _Pragma("unroll") for (int k = 0; k < 2; ++k) dst[m][k] = *(const LAS bf16x8*)(lds + PG8_SA(b, h) + aoff + m * 2048 + k * 1024); } while (0)
; #define PG8_LDB(dst, b, h) do { _Pragma("unroll") for (int n = 0; n < 2; ++n) _Pragma("unroll") for (int k = 0; k < 2; ++k) dst[n][k] = *(const LAS bf16x8*)(lds + PG8_SB(b, h) + boff + n * 2048 + k * 1024); } while (0)
; #define PG8_MMA(ai, bj, At, Bt) do { __builtin_amdgcn_s_setprio(1); _Pragma("unroll") for (int m = 0; m < 4; ++m) _Pragma("unroll") for (int n = 0; n < 2; ++n) _Pragma("unroll") for (int k = 0; k < 2; ++k) \
;         acc[ai][bj][m][n] = __builtin_amdgcn_mfma_f32_16x16x32_bf16(Bt[n][k], At[m][k], acc[ai][bj][m][n], 0, 0, 0); __builtin_amdgcn_s_setprio(0); } while (0)
; #define PG8_WAIT_V(n) asm volatile("s_waitcnt vmcnt(" #n ")" ::: "memory")
; #define PG8_WAIT_L(n) asm volatile("s_waitcnt lgkmcnt(" #n ")" ::: "memory")
; #define PG8_BAR __builtin_amdgcn_s_barrier()
; #define PG8_SCHED __builtin_amdgcn_sched_barrier(0)
; template <class Epi>
; DI void gemm_phase(LAS unsigned char* lds, const Gemm g, const StaticOrder& S, const Epi& E) {
;     ...
;             PG8_LDB(B0, 0, 0); PG8_LDB(B1, 0, 1); PG8_SCHED; PG8_LDA(At, 0, 0); PG8_STAGE(PG8_SA(1, 1), a1 + hstep, voffA);
;             PG8_WAIT_V(8); PG8_WAIT_L(0); PG8_BAR; PG8_MMA(0, 0, At, B0); PG8_MMA(0, 1, At, B1); PG8_BAR; PG8_SCHED;
;             PG8_LDA(At, 0, 1); PG8_STAGE(PG8_SB(0, 0), b2, voffB); PG8_STAGE(PG8_SB(0, 1), b2 + hstep, voffB); PG8_STAGE(PG8_SA(0, 0), a2, voffA);
;             PG8_WAIT_V(8); PG8_WAIT_L(0); PG8_BAR; PG8_MMA(1, 0, At, B0); PG8_MMA(1, 1, At, B1); PG8_BAR; PG8_SCHED;
.LBB0_782:
	s_add_u32 s73, s60, 0x100
	s_addc_u32 s91, s61, 0
	s_mov_b32 s93, -2
	v_readfirstlane_b32 s101, v242
	s_nop 3
	s_lshr_b32 s101, s101, 8
	s_cmp_eq_u32 s101, 0
	s_cbranch_scc0 .Lsp_0
	s_setprio 1
.Lsp_0:
	s_add_u32 s60, s58, 0x100
	s_addc_u32 s61, s59, 0
	s_add_i32 s18, 0, 0x10000
	s_cmp_eq_u32 s93, 40
	s_cselect_b32 s65, s9, s61
	s_cselect_b32 s64, s8, s60
	s_cselect_b32 s63, s57, s91
	s_cselect_b32 s62, s56, s73
	s_add_i32 s81, 0, 0x14000
	v_add_u32_e32 v126, s18, v195
	v_add_u32_e32 v154, s81, v195
	ds_read_b128 v[114:117], v126
	ds_read_b128 v[118:121], v126 offset:1024
	ds_read_b128 v[122:125], v126 offset:2048
	ds_read_b128 v[126:129], v126 offset:3072
	ds_read_b128 v[134:137], v154
	ds_read_b128 v[138:141], v154 offset:1024
	ds_read_b128 v[146:149], v154 offset:2048
	ds_read_b128 v[154:157], v154 offset:3072
	v_lshl_add_u64 v[204:205], s[58:59], 0, v[184:185]
	s_add_i32 m0, s66, 0xc000
	ds_read_b128 v[162:165], v217
	ds_read_b128 v[166:169], v217 offset:1024
	ds_read_b128 v[170:173], v217 offset:2048
	ds_read_b128 v[174:177], v217 offset:3072
	ds_read_b128 v[186:189], v217 offset:4096
	ds_read_b128 v[190:193], v217 offset:5120
	ds_read_b128 v[200:203], v217 offset:6144
	ds_read_b128 v[206:209], v217 offset:7168
	global_load_lds_dwordx4 v[204:205], off
	v_lshl_add_u64 v[204:205], s[58:59], 0, v[182:183]
	s_add_i32 m0, s66, 0xe000
	s_nop 0
	global_load_lds_dwordx4 v[204:205], off
	s_waitcnt vmcnt(8)
	s_waitcnt lgkmcnt(0)
	s_barrier
	s_waitcnt lgkmcnt(0)
	v_mfma_f32_16x16x32_bf16 v[158:161], v[114:117], v[162:165], 0
	v_mfma_f32_16x16x32_bf16 v[150:153], v[122:125], v[162:165], 0
	v_mfma_f32_16x16x32_bf16 v[110:113], v[114:117], v[170:173], 0
	v_mfma_f32_16x16x32_bf16 v[106:109], v[122:125], v[170:173], 0
	v_mfma_f32_16x16x32_bf16 v[94:97], v[114:117], v[186:189], 0
	v_mfma_f32_16x16x32_bf16 v[90:93], v[122:125], v[186:189], 0
	v_mfma_f32_16x16x32_bf16 v[78:81], v[114:117], v[200:203], 0
	v_mfma_f32_16x16x32_bf16 v[74:77], v[122:125], v[200:203], 0
	v_mfma_f32_16x16x32_bf16 v[158:161], v[118:121], v[166:169], v[158:161]
	v_mfma_f32_16x16x32_bf16 v[150:153], v[126:129], v[166:169], v[150:153]
	v_mfma_f32_16x16x32_bf16 v[110:113], v[118:121], v[174:177], v[110:113]
	v_mfma_f32_16x16x32_bf16 v[106:109], v[126:129], v[174:177], v[106:109]
	v_mfma_f32_16x16x32_bf16 v[94:97], v[118:121], v[190:193], v[94:97]
	v_mfma_f32_16x16x32_bf16 v[90:93], v[126:129], v[190:193], v[90:93]
	v_mfma_f32_16x16x32_bf16 v[78:81], v[118:121], v[206:209], v[78:81]
	v_mfma_f32_16x16x32_bf16 v[74:77], v[126:129], v[206:209], v[74:77]
	v_mfma_f32_16x16x32_bf16 v[142:145], v[134:137], v[162:165], 0
	v_mfma_f32_16x16x32_bf16 v[130:133], v[146:149], v[162:165], 0
	v_mfma_f32_16x16x32_bf16 v[102:105], v[134:137], v[170:173], 0
	v_mfma_f32_16x16x32_bf16 v[98:101], v[146:149], v[170:173], 0
	v_mfma_f32_16x16x32_bf16 v[86:89], v[134:137], v[186:189], 0
	v_mfma_f32_16x16x32_bf16 v[82:85], v[146:149], v[186:189], 0
	v_mfma_f32_16x16x32_bf16 v[70:73], v[134:137], v[200:203], 0
	v_mfma_f32_16x16x32_bf16 v[66:69], v[146:149], v[200:203], 0
	v_mfma_f32_16x16x32_bf16 v[142:145], v[138:141], v[166:169], v[142:145]
	v_mfma_f32_16x16x32_bf16 v[130:133], v[154:157], v[166:169], v[130:133]
	v_mfma_f32_16x16x32_bf16 v[102:105], v[138:141], v[174:177], v[102:105]
	v_mfma_f32_16x16x32_bf16 v[98:101], v[154:157], v[174:177], v[98:101]
	v_mfma_f32_16x16x32_bf16 v[86:89], v[138:141], v[190:193], v[86:89]
	v_mfma_f32_16x16x32_bf16 v[82:85], v[154:157], v[190:193], v[82:85]
	v_mfma_f32_16x16x32_bf16 v[70:73], v[138:141], v[206:209], v[70:73]
	v_mfma_f32_16x16x32_bf16 v[66:69], v[154:157], v[206:209], v[66:69]
	s_barrier
	s_add_i32 s18, s18, s37
	v_lshl_add_u64 v[204:205], s[62:63], 0, v[178:179]
	s_mov_b32 m0, s18
	ds_read_b128 v[162:165], v217 offset:16384
	ds_read_b128 v[166:169], v217 offset:17408
	ds_read_b128 v[170:173], v217 offset:18432
	ds_read_b128 v[174:177], v217 offset:19456
	ds_read_b128 v[186:189], v217 offset:20480
	ds_read_b128 v[190:193], v217 offset:21504
	ds_read_b128 v[200:203], v217 offset:22528
	ds_read_b128 v[206:209], v217 offset:23552
	global_load_lds_dwordx4 v[204:205], off
	s_add_i32 m0, s18, 0x2000
	s_add_u32 s18, s62, 0xb0000
	v_lshl_add_u64 v[210:211], s[62:63], 0, v[180:181]
	s_addc_u32 s19, s63, 0
	s_add_i32 s58, s81, s37
	global_load_lds_dwordx4 v[210:211], off
	v_lshl_add_u64 v[212:213], s[18:19], 0, v[178:179]
	s_mov_b32 m0, s58
	v_lshl_add_u64 v[214:215], s[64:65], 0, v[180:181]
	global_load_lds_dwordx4 v[212:213], off
	v_lshl_add_u64 v[212:213], s[18:19], 0, v[180:181]
	s_add_i32 m0, s58, 0x2000
	s_nop 0
	global_load_lds_dwordx4 v[212:213], off
	v_lshl_add_u64 v[212:213], s[64:65], 0, v[178:179]
	s_mov_b32 m0, s66
	s_nop 0
	global_load_lds_dwordx4 v[212:213], off
	s_mov_b32 m0, s67
	s_nop 0
	global_load_lds_dwordx4 v[214:215], off
	s_waitcnt vmcnt(8)
	s_waitcnt lgkmcnt(0)
	s_barrier
	s_waitcnt lgkmcnt(0)
	v_mfma_f32_16x16x32_bf16 v[62:65], v[114:117], v[162:165], 0
	v_mfma_f32_16x16x32_bf16 v[58:61], v[122:125], v[162:165], 0
	v_mfma_f32_16x16x32_bf16 v[46:49], v[114:117], v[170:173], 0
	v_mfma_f32_16x16x32_bf16 v[42:45], v[122:125], v[170:173], 0
	v_mfma_f32_16x16x32_bf16 v[30:33], v[114:117], v[186:189], 0
	v_mfma_f32_16x16x32_bf16 v[26:29], v[122:125], v[186:189], 0
	v_mfma_f32_16x16x32_bf16 v[14:17], v[114:117], v[200:203], 0
	v_mfma_f32_16x16x32_bf16 v[10:13], v[122:125], v[200:203], 0
	v_mfma_f32_16x16x32_bf16 v[62:65], v[118:121], v[166:169], v[62:65]
	v_mfma_f32_16x16x32_bf16 v[58:61], v[126:129], v[166:169], v[58:61]
	v_mfma_f32_16x16x32_bf16 v[46:49], v[118:121], v[174:177], v[46:49]
	v_mfma_f32_16x16x32_bf16 v[42:45], v[126:129], v[174:177], v[42:45]
	v_mfma_f32_16x16x32_bf16 v[30:33], v[118:121], v[190:193], v[30:33]
	v_mfma_f32_16x16x32_bf16 v[26:29], v[126:129], v[190:193], v[26:29]
	v_mfma_f32_16x16x32_bf16 v[14:17], v[118:121], v[206:209], v[14:17]
	v_mfma_f32_16x16x32_bf16 v[10:13], v[126:129], v[206:209], v[10:13]
	v_mfma_f32_16x16x32_bf16 v[54:57], v[134:137], v[162:165], 0
	v_mfma_f32_16x16x32_bf16 v[50:53], v[146:149], v[162:165], 0
	v_mfma_f32_16x16x32_bf16 v[38:41], v[134:137], v[170:173], 0
	v_mfma_f32_16x16x32_bf16 v[34:37], v[146:149], v[170:173], 0
	v_mfma_f32_16x16x32_bf16 v[22:25], v[134:137], v[186:189], 0
	v_mfma_f32_16x16x32_bf16 v[18:21], v[146:149], v[186:189], 0
	v_mfma_f32_16x16x32_bf16 v[6:9], v[134:137], v[200:203], 0
	v_mfma_f32_16x16x32_bf16 v[2:5], v[146:149], v[200:203], 0
	v_mfma_f32_16x16x32_bf16 v[54:57], v[138:141], v[166:169], v[54:57]
	v_mfma_f32_16x16x32_bf16 v[50:53], v[154:157], v[166:169], v[50:53]
	v_mfma_f32_16x16x32_bf16 v[38:41], v[138:141], v[174:177], v[38:41]
	v_mfma_f32_16x16x32_bf16 v[34:37], v[154:157], v[174:177], v[34:37]
	v_mfma_f32_16x16x32_bf16 v[22:25], v[138:141], v[190:193], v[22:25]
	v_mfma_f32_16x16x32_bf16 v[18:21], v[154:157], v[190:193], v[18:21]
	v_mfma_f32_16x16x32_bf16 v[6:9], v[138:141], v[206:209], v[6:9]
	v_mfma_f32_16x16x32_bf16 v[2:5], v[154:157], v[206:209], v[2:5]
	s_barrier
	s_branch .Lp3_down

; #define PG8_STAGE(bufoff, gbase, voff) do { _Pragma("unroll") for (int _i = 0; _i < 2; ++_i) \
;         __builtin_amdgcn_global_load_lds((const unsigned*)((const char*)(gbase) + (voff)[_i]), (LAS unsigned*)(lds + (bufoff) + ldsw + _i * 8192), 16, 0, 0); } while (0)
; #define PG8_LDA(dst, b, h) do { _Pragma("unroll") for (int m = 0; m < 4; ++m) _Pragma("unroll") for (int k = 0; k < 2; ++k) dst[m][k] = *(const LAS bf16x8*)(lds + PG8_SA(b, h) + aoff + m * 2048 + k * 1024); } while (0)
; #define PG8_LDB(dst, b, h) do { _Pragma("unroll") for (int n = 0; n < 2; ++n) _Pragma("unroll") for (int k = 0; k < 2; ++k) dst[n][k] = *(const LAS bf16x8*)(lds + PG8_SB(b, h) + boff + n * 2048 + k * 1024); } while (0)
; #define PG8_MMA(ai, bj, At, Bt) do { __builtin_amdgcn_s_setprio(1); _Pragma("unroll") for (int m = 0; m < 4; ++m) _Pragma("unroll") for (int n = 0; n < 2; ++n) _Pragma("unroll") for (int k = 0; k < 2; ++k) \
;         acc[ai][bj][m][n] = __builtin_amdgcn_mfma_f32_16x16x32_bf16(Bt[n][k], At[m][k], acc[ai][bj][m][n], 0, 0, 0); __builtin_amdgcn_s_setprio(0); } while (0)
; #define PG8_WAIT_V(n) asm volatile("s_waitcnt vmcnt(" #n ")" ::: "memory")
; #define PG8_WAIT_L(n) asm volatile("s_waitcnt lgkmcnt(" #n ")" ::: "memory")
; #define PG8_BAR __builtin_amdgcn_s_barrier()
; #define PG8_SCHED __builtin_amdgcn_sched_barrier(0)
; template <class Epi>
; DI void gemm_phase(LAS unsigned char* lds, const Gemm g, const StaticOrder& S, const Epi& E) {
;     ...
;             PG8_LDB(B0, 1, 0); PG8_LDB(B1, 1, 1); PG8_SCHED; PG8_LDA(At, 1, 0); PG8_STAGE(PG8_SA(0, 1), a2 + hstep, voffA);
;             PG8_WAIT_V(8); PG8_WAIT_L(0); PG8_BAR; PG8_MMA(0, 0, At, B0); PG8_MMA(0, 1, At, B1); PG8_BAR; PG8_SCHED;
.Lp3_down:
	s_add_i32 s58, 0, 0x18000
	s_add_i32 s59, 0, 0x1c000
	v_add_u32_e32 v126, s58, v195
	v_add_u32_e32 v154, s59, v195
	ds_read_b128 v[114:117], v126
	ds_read_b128 v[118:121], v126 offset:1024
	ds_read_b128 v[122:125], v126 offset:2048
	ds_read_b128 v[126:129], v126 offset:3072
	ds_read_b128 v[134:137], v154
	ds_read_b128 v[138:141], v154 offset:1024
	ds_read_b128 v[146:149], v154 offset:2048
	ds_read_b128 v[154:157], v154 offset:3072
	s_add_u32 s18, s64, 0xb0000
	s_addc_u32 s19, s65, 0
	s_mov_b32 m0, s68
	v_lshl_add_u64 v[218:219], s[18:19], 0, v[178:179]
	ds_read_b128 v[162:165], v217 offset:32768
	ds_read_b128 v[166:169], v217 offset:33792
	ds_read_b128 v[170:173], v217 offset:34816
	ds_read_b128 v[174:177], v217 offset:35840
	ds_read_b128 v[186:189], v217 offset:36864
	ds_read_b128 v[190:193], v217 offset:37888
	ds_read_b128 v[200:203], v217 offset:38912
	ds_read_b128 v[206:209], v217 offset:39936
	global_load_lds_dwordx4 v[218:219], off
	v_lshl_add_u64 v[218:219], s[18:19], 0, v[180:181]
	s_mov_b32 m0, s69
	s_nop 0
	global_load_lds_dwordx4 v[218:219], off
	s_waitcnt vmcnt(8)
	s_waitcnt lgkmcnt(0)
	s_barrier
	s_waitcnt lgkmcnt(0)
	v_mfma_f32_16x16x32_bf16 v[158:161], v[114:117], v[162:165], v[158:161]
	v_mfma_f32_16x16x32_bf16 v[150:153], v[122:125], v[162:165], v[150:153]
	v_mfma_f32_16x16x32_bf16 v[110:113], v[114:117], v[170:173], v[110:113]
	v_mfma_f32_16x16x32_bf16 v[106:109], v[122:125], v[170:173], v[106:109]
	v_mfma_f32_16x16x32_bf16 v[94:97], v[114:117], v[186:189], v[94:97]
	v_mfma_f32_16x16x32_bf16 v[90:93], v[122:125], v[186:189], v[90:93]
	v_mfma_f32_16x16x32_bf16 v[78:81], v[114:117], v[200:203], v[78:81]
	v_mfma_f32_16x16x32_bf16 v[74:77], v[122:125], v[200:203], v[74:77]
	v_mfma_f32_16x16x32_bf16 v[158:161], v[118:121], v[166:169], v[158:161]
	v_mfma_f32_16x16x32_bf16 v[150:153], v[126:129], v[166:169], v[150:153]
	v_mfma_f32_16x16x32_bf16 v[110:113], v[118:121], v[174:177], v[110:113]
	v_mfma_f32_16x16x32_bf16 v[106:109], v[126:129], v[174:177], v[106:109]
	v_mfma_f32_16x16x32_bf16 v[94:97], v[118:121], v[190:193], v[94:97]
	v_mfma_f32_16x16x32_bf16 v[90:93], v[126:129], v[190:193], v[90:93]
	v_mfma_f32_16x16x32_bf16 v[78:81], v[118:121], v[206:209], v[78:81]
	v_mfma_f32_16x16x32_bf16 v[74:77], v[126:129], v[206:209], v[74:77]
	v_mfma_f32_16x16x32_bf16 v[142:145], v[134:137], v[162:165], v[142:145]
	v_mfma_f32_16x16x32_bf16 v[130:133], v[146:149], v[162:165], v[130:133]
	v_mfma_f32_16x16x32_bf16 v[102:105], v[134:137], v[170:173], v[102:105]
	v_mfma_f32_16x16x32_bf16 v[98:101], v[146:149], v[170:173], v[98:101]
	v_mfma_f32_16x16x32_bf16 v[86:89], v[134:137], v[186:189], v[86:89]
	v_mfma_f32_16x16x32_bf16 v[82:85], v[146:149], v[186:189], v[82:85]
	v_mfma_f32_16x16x32_bf16 v[70:73], v[134:137], v[200:203], v[70:73]
	v_mfma_f32_16x16x32_bf16 v[66:69], v[146:149], v[200:203], v[66:69]
	v_mfma_f32_16x16x32_bf16 v[142:145], v[138:141], v[166:169], v[142:145]
	v_mfma_f32_16x16x32_bf16 v[130:133], v[154:157], v[166:169], v[130:133]
	v_mfma_f32_16x16x32_bf16 v[102:105], v[138:141], v[174:177], v[102:105]
	v_mfma_f32_16x16x32_bf16 v[98:101], v[154:157], v[174:177], v[98:101]
	v_mfma_f32_16x16x32_bf16 v[86:89], v[138:141], v[190:193], v[86:89]
	v_mfma_f32_16x16x32_bf16 v[82:85], v[154:157], v[190:193], v[82:85]
	v_mfma_f32_16x16x32_bf16 v[70:73], v[138:141], v[206:209], v[70:73]
	v_mfma_f32_16x16x32_bf16 v[66:69], v[154:157], v[206:209], v[66:69]
	s_barrier
; #define PG8_STAGE(bufoff, gbase, voff) do { _Pragma("unroll") for (int _i = 0; _i < 2; ++_i) \
;         __builtin_amdgcn_global_load_lds((const unsigned*)((const char*)(gbase) + (voff)[_i]), (LAS unsigned*)(lds + (bufoff) + ldsw + _i * 8192), 16, 0, 0); } while (0)
; #define PG8_LDA(dst, b, h) do { _Pragma("unroll") for (int m = 0; m < 4; ++m) _Pragma("unroll") for (int k = 0; k < 2; ++k) dst[m][k] = *(const LAS bf16x8*)(lds + PG8_SA(b, h) + aoff + m * 2048 + k * 1024); } while (0)
; #define PG8_MMA(ai, bj, At, Bt) do { __builtin_amdgcn_s_setprio(1); _Pragma("unroll") for (int m = 0; m < 4; ++m) _Pragma("unroll") for (int n = 0; n < 2; ++n) _Pragma("unroll") for (int k = 0; k < 2; ++k) \
;         acc[ai][bj][m][n] = __builtin_amdgcn_mfma_f32_16x16x32_bf16(Bt[n][k], At[m][k], acc[ai][bj][m][n], 0, 0, 0); __builtin_amdgcn_s_setprio(0); } while (0)
; #define PG8_WAIT_V(n) asm volatile("s_waitcnt vmcnt(" #n ")" ::: "memory")
; #define PG8_WAIT_L(n) asm volatile("s_waitcnt lgkmcnt(" #n ")" ::: "memory")
; #define PG8_BAR __builtin_amdgcn_s_barrier()
; #define PG8_SCHED __builtin_amdgcn_sched_barrier(0)
; template <class Epi>
; DI void gemm_phase(LAS unsigned char* lds, const Gemm g, const StaticOrder& S, const Epi& E) {
;     ...
;             PG8_LDA(At, 1, 1); PG8_STAGE(PG8_SB(1, 0), b3, voffB); PG8_STAGE(PG8_SB(1, 1), b3 + hstep, voffB); PG8_STAGE(PG8_SA(1, 0), a3, voffA);
;             PG8_WAIT_V(8); PG8_WAIT_L(0); PG8_BAR; PG8_MMA(1, 0, At, B0); PG8_MMA(1, 1, At, B1); PG8_BAR; PG8_SCHED;
;         }
;         if (wr == 0) PG8_BAR;
	s_add_i32 s18, s58, s37
	v_lshl_add_u64 v[204:205], v[204:205], 0, s[20:21]
	s_mov_b32 m0, s18
	ds_read_b128 v[162:165], v217 offset:49152
	ds_read_b128 v[166:169], v217 offset:50176
	ds_read_b128 v[170:173], v217 offset:51200
	ds_read_b128 v[174:177], v217 offset:52224
	ds_read_b128 v[186:189], v217 offset:53248
	ds_read_b128 v[190:193], v217 offset:54272
	ds_read_b128 v[200:203], v217 offset:55296
	ds_read_b128 v[206:209], v217 offset:56320
	global_load_lds_dwordx4 v[204:205], off
	s_add_i32 m0, s18, 0x2000
	s_add_u32 s18, s62, 0xb0080
	v_lshl_add_u64 v[204:205], v[210:211], 0, s[20:21]
	s_addc_u32 s19, s63, 0
	s_add_i32 s58, s59, s37
	global_load_lds_dwordx4 v[204:205], off
	v_lshl_add_u64 v[204:205], s[18:19], 0, v[178:179]
	s_mov_b32 m0, s58
	s_nop 0
	global_load_lds_dwordx4 v[204:205], off
	v_lshl_add_u64 v[204:205], s[18:19], 0, v[180:181]
	s_add_i32 m0, s58, 0x2000
	s_nop 0
	global_load_lds_dwordx4 v[204:205], off
	v_lshl_add_u64 v[204:205], v[212:213], 0, s[20:21]
	s_mov_b32 m0, s71
	s_nop 0
	global_load_lds_dwordx4 v[204:205], off
	v_lshl_add_u64 v[204:205], v[214:215], 0, s[20:21]
	s_mov_b32 m0, s17
	s_nop 0
	global_load_lds_dwordx4 v[204:205], off
	s_waitcnt vmcnt(8)
	s_waitcnt lgkmcnt(0)
	s_barrier
	s_waitcnt lgkmcnt(0)
	v_mfma_f32_16x16x32_bf16 v[62:65], v[114:117], v[162:165], v[62:65]
	v_mfma_f32_16x16x32_bf16 v[58:61], v[122:125], v[162:165], v[58:61]
	v_mfma_f32_16x16x32_bf16 v[46:49], v[114:117], v[170:173], v[46:49]
	v_mfma_f32_16x16x32_bf16 v[42:45], v[122:125], v[170:173], v[42:45]
	v_mfma_f32_16x16x32_bf16 v[30:33], v[114:117], v[186:189], v[30:33]
	v_mfma_f32_16x16x32_bf16 v[26:29], v[122:125], v[186:189], v[26:29]
	v_mfma_f32_16x16x32_bf16 v[14:17], v[114:117], v[200:203], v[14:17]
	v_mfma_f32_16x16x32_bf16 v[10:13], v[122:125], v[200:203], v[10:13]
	v_mfma_f32_16x16x32_bf16 v[62:65], v[118:121], v[166:169], v[62:65]
	v_mfma_f32_16x16x32_bf16 v[58:61], v[126:129], v[166:169], v[58:61]
	v_mfma_f32_16x16x32_bf16 v[46:49], v[118:121], v[174:177], v[46:49]
	v_mfma_f32_16x16x32_bf16 v[42:45], v[126:129], v[174:177], v[42:45]
	v_mfma_f32_16x16x32_bf16 v[30:33], v[118:121], v[190:193], v[30:33]
	v_mfma_f32_16x16x32_bf16 v[26:29], v[126:129], v[190:193], v[26:29]
	v_mfma_f32_16x16x32_bf16 v[14:17], v[118:121], v[206:209], v[14:17]
	v_mfma_f32_16x16x32_bf16 v[10:13], v[126:129], v[206:209], v[10:13]
	v_mfma_f32_16x16x32_bf16 v[54:57], v[134:137], v[162:165], v[54:57]
	v_mfma_f32_16x16x32_bf16 v[50:53], v[146:149], v[162:165], v[50:53]
	v_mfma_f32_16x16x32_bf16 v[38:41], v[134:137], v[170:173], v[38:41]
	v_mfma_f32_16x16x32_bf16 v[34:37], v[146:149], v[170:173], v[34:37]
	v_mfma_f32_16x16x32_bf16 v[22:25], v[134:137], v[186:189], v[22:25]
	v_mfma_f32_16x16x32_bf16 v[18:21], v[146:149], v[186:189], v[18:21]
	v_mfma_f32_16x16x32_bf16 v[6:9], v[134:137], v[200:203], v[6:9]
	v_mfma_f32_16x16x32_bf16 v[2:5], v[146:149], v[200:203], v[2:5]
	v_mfma_f32_16x16x32_bf16 v[54:57], v[138:141], v[166:169], v[54:57]
	v_mfma_f32_16x16x32_bf16 v[50:53], v[154:157], v[166:169], v[50:53]
	v_mfma_f32_16x16x32_bf16 v[38:41], v[138:141], v[174:177], v[38:41]
	v_mfma_f32_16x16x32_bf16 v[34:37], v[154:157], v[174:177], v[34:37]
	v_mfma_f32_16x16x32_bf16 v[22:25], v[138:141], v[190:193], v[22:25]
	v_mfma_f32_16x16x32_bf16 v[18:21], v[154:157], v[190:193], v[18:21]
	v_mfma_f32_16x16x32_bf16 v[6:9], v[138:141], v[206:209], v[6:9]
	v_mfma_f32_16x16x32_bf16 v[2:5], v[154:157], v[206:209], v[2:5]
	s_barrier
	s_add_i32 s93, s93, 2
	s_add_u32 s73, s73, 0x100
	s_addc_u32 s91, s91, 0
	s_cmp_gt_u32 s93, 41
	s_mov_b64 s[58:59], s[60:61]
	s_cbranch_scc0 .LBB0_783
	s_setprio 0
	s_and_b64 vcc, exec, s[54:55]
	s_cbranch_vccz .LBB0_786
	s_barrier
